# chunk C0 slices: next slice's staging loads issued before the MFMA section; dilated softmax: 36 per-site bias LDS lookups replaced by one prefetch block per slab
# speedup vs baseline: 1.0094x; 1.0021x over previous
.LBB0_1266:
	s_or_b64 exec, exec, s[56:57]
	ds_read_b32 v0, v75 offset:51648
	s_cmp_gt_u32 s60, 63
	s_cselect_b64 s[38:39], -1, 0
	s_and_b64 s[56:57], s[38:39], exec
	s_mul_i32 s14, s16, 0x13800
	s_waitcnt lgkmcnt(0)
	v_sub_f32_e32 v2, v0, v8
	v_mul_f32_e32 v2, 0x3fb8aa3b, v2
	v_exp_f32_e32 v2, v2
	v_sub_f32_e32 v3, v0, v9
	v_mul_f32_e32 v3, 0x3fb8aa3b, v3
	v_exp_f32_e32 v3, v3
	v_mul_f32_e32 v2, v36, v2
	v_cndmask_b32_e64 v2, v2, 0, s[70:71]
	v_sub_f32_e32 v8, v0, v10
	v_bfe_u32 v9, v2, 16, 1
	v_mul_f32_e32 v8, 0x3fb8aa3b, v8
	v_add3_u32 v2, v2, v9, s64
	ds_write_b16_d16_hi v104, v2 offset:56032
	v_exp_f32_e32 v2, v8
	v_sub_f32_e32 v0, v0, v11
	v_mul_f32_e32 v0, 0x3fb8aa3b, v0
	v_mul_f32_e32 v3, v37, v3
	v_exp_f32_e32 v0, v0
	v_cndmask_b32_e64 v3, v3, 0, s[72:73]
	v_bfe_u32 v8, v3, 16, 1
	v_mul_f32_e32 v2, v38, v2
	v_add3_u32 v3, v3, v8, s64
	v_cndmask_b32_e64 v2, v2, 0, s[80:81]
	v_readlane_b32 s40, v252, 6
	ds_write_b16_d16_hi v104, v3 offset:56304
	v_bfe_u32 v3, v2, 16, 1
	v_mul_f32_e32 v0, v39, v0
	s_cselect_b32 s61, 0, 3
	s_mul_hi_i32 s56, s16, 0x13800
	s_add_u32 s14, s40, s14
	v_readlane_b32 s40, v252, 7
	v_add3_u32 v2, v2, v3, s64
	v_cndmask_b32_e64 v0, v0, 0, s[82:83]
	s_addc_u32 s58, s40, s56
	s_mul_hi_i32 s56, s68, 0x13800
	s_mul_i32 s68, s68, 0x13800
	v_readlane_b32 s40, v252, 16
	ds_write_b16_d16_hi v104, v2 offset:56576
	v_bfe_u32 v2, v0, 16, 1
	s_add_u32 s59, s40, s68
	v_readlane_b32 s40, v252, 17
	v_add3_u32 v0, v0, v2, s64
	s_addc_u32 s60, s40, s56
	v_readlane_b32 s40, v252, 14
	v_mov_b32_e32 v2, v1
	v_mov_b32_e32 v3, v1
	ds_write_b16_d16_hi v104, v0 offset:56848
	s_add_u32 s18, s40, s18
	v_readlane_b32 s40, v252, 15
	v_mov_b32_e32 v0, v1
	v_mov_b64_e32 v[54:55], v[2:3]
	v_mov_b64_e32 v[50:51], v[2:3]
	v_mov_b64_e32 v[46:47], v[2:3]
	v_mov_b64_e32 v[42:43], v[2:3]
	v_mov_b64_e32 v[38:39], v[2:3]
	v_mov_b64_e32 v[34:35], v[2:3]
	v_mov_b64_e32 v[30:31], v[2:3]
	v_mov_b64_e32 v[26:27], v[2:3]
	v_mov_b64_e32 v[22:23], v[2:3]
	v_mov_b64_e32 v[18:19], v[2:3]
	v_mov_b64_e32 v[14:15], v[2:3]
	v_mov_b64_e32 v[10:11], v[2:3]
	v_mov_b64_e32 v[58:59], v[2:3]
	s_addc_u32 s19, s40, s19
	v_mov_b64_e32 v[52:53], v[0:1]
	v_mov_b64_e32 v[48:49], v[0:1]
	v_mov_b64_e32 v[44:45], v[0:1]
	v_mov_b64_e32 v[40:41], v[0:1]
	v_mov_b64_e32 v[36:37], v[0:1]
	v_mov_b64_e32 v[32:33], v[0:1]
	v_mov_b64_e32 v[28:29], v[0:1]
	v_mov_b64_e32 v[24:25], v[0:1]
	v_mov_b64_e32 v[20:21], v[0:1]
	v_mov_b64_e32 v[16:17], v[0:1]
	v_mov_b64_e32 v[12:13], v[0:1]
	v_mov_b64_e32 v[8:9], v[0:1]
	v_mov_b64_e32 v[56:57], v[0:1]
	s_mov_b32 s98, 0

.LBB0_1270:
	s_mov_b64 s[68:69], 0x6000
	s_cmp_lg_u32 s98, 0
	s_cbranch_scc1 .Lc0_have
	global_load_dwordx4 v[232:235], v[2:3], off
	v_lshl_add_u64 v[2:3], v[2:3], 0, s[68:69]
	global_load_dwordx4 v[236:239], v[2:3], off
	v_lshl_add_u64 v[2:3], v[2:3], 0, s[68:69]
	global_load_dwordx4 v[240:243], v[2:3], off
	v_lshl_add_u64 v[2:3], v[2:3], 0, s[68:69]
	v_cmp_gt_u32_e32 vcc, 0x80, v176
	s_and_saveexec_b64 s[56:57], vcc
	global_load_dwordx4 v[244:247], v[2:3], off
	s_or_b64 exec, exec, s[56:57]
.Lc0_have:
	s_waitcnt vmcnt(0)
	ds_write_b128 v0, v[232:235]
	ds_write_b128 v0, v[236:239] offset:9216
	ds_write_b128 v0, v[240:243] offset:18432
	v_cmp_gt_u32_e32 vcc, 0x80, v176
	s_and_saveexec_b64 s[56:57], vcc
	ds_write_b128 v0, v[244:247] offset:27648
	s_or_b64 exec, exec, s[56:57]
	s_mov_b32 s98, 0
	s_add_i32 s99, s61, 1
	s_add_i32 s32, s61, -2
	s_cmp_gt_u32 s99, 5
	s_cbranch_scc1 .Lc0_nopf
	s_cmp_lt_u32 s99, 3
	s_cselect_b32 vcc_lo, s59, s14
	s_cselect_b32 vcc_hi, s60, s58
	s_cselect_b32 s99, s99, s32
	s_lshl_b32 s99, s99, 7
	v_lshl_add_u64 v[2:3], vcc, 0, v[86:87]
	v_mov_b32_e32 v248, s99
	v_mov_b32_e32 v249, 0
	v_lshl_add_u64 v[2:3], v[2:3], 0, v[248:249]
	global_load_dwordx4 v[232:235], v[2:3], off
	v_lshl_add_u64 v[2:3], v[2:3], 0, s[68:69]
	global_load_dwordx4 v[236:239], v[2:3], off
	v_lshl_add_u64 v[2:3], v[2:3], 0, s[68:69]
	global_load_dwordx4 v[240:243], v[2:3], off
	v_lshl_add_u64 v[2:3], v[2:3], 0, s[68:69]
	v_cmp_gt_u32_e32 vcc, 0x80, v176
	s_and_saveexec_b64 s[56:57], vcc
	global_load_dwordx4 v[244:247], v[2:3], off
	s_or_b64 exec, exec, s[56:57]
	s_mov_b32 s98, 1
.Lc0_nopf:
	s_movk_i32 s68, 0x47f
	s_or_b64 exec, exec, s[56:57]
	v_lshl_add_u32 v0, v92, 7, v71
	s_waitcnt lgkmcnt(0)
	s_barrier
	ds_read_b128 v[92:95], v0
	ds_read_b128 v[180:183], v105
	ds_read_b128 v[184:187], v106
	ds_read_b128 v[188:191], v106 offset:2304
	ds_read_b128 v[192:195], v106 offset:4608
	ds_read_b128 v[196:199], v106 offset:6912
	ds_read_b128 v[200:203], v106 offset:9216
	ds_read_b128 v[204:207], v106 offset:11520
	ds_read_b128 v[208:211], v106 offset:13824
	ds_read_b128 v[212:215], v105 offset:18432
	ds_read_b128 v[216:219], v105 offset:20736
	ds_read_b128 v[220:223], v105 offset:23040
	ds_read_b128 v[224:227], v105 offset:25344
	ds_read_b128 v[228:231], v105 offset:27648
	s_add_i32 s56, s61, 1
	s_cmp_gt_u32 s61, 4
	s_waitcnt lgkmcnt(12)
	v_mfma_f32_16x16x32_bf16 v[8:11], v[92:95], v[180:183], v[8:11]
	s_waitcnt lgkmcnt(11)
	v_mfma_f32_16x16x32_bf16 v[12:15], v[92:95], v[184:187], v[12:15]
	s_waitcnt lgkmcnt(10)
	v_mfma_f32_16x16x32_bf16 v[16:19], v[92:95], v[188:191], v[16:19]
	s_waitcnt lgkmcnt(9)
	v_mfma_f32_16x16x32_bf16 v[20:23], v[92:95], v[192:195], v[20:23]
	s_waitcnt lgkmcnt(8)
	v_mfma_f32_16x16x32_bf16 v[24:27], v[92:95], v[196:199], v[24:27]
	s_waitcnt lgkmcnt(7)
	v_mfma_f32_16x16x32_bf16 v[28:31], v[92:95], v[200:203], v[28:31]
	s_waitcnt lgkmcnt(6)
	v_mfma_f32_16x16x32_bf16 v[32:35], v[92:95], v[204:207], v[32:35]
	s_waitcnt lgkmcnt(5)
	v_mfma_f32_16x16x32_bf16 v[36:39], v[92:95], v[208:211], v[36:39]
	s_waitcnt lgkmcnt(4)
	v_mfma_f32_16x16x32_bf16 v[40:43], v[92:95], v[212:215], v[40:43]
	s_waitcnt lgkmcnt(3)
	v_mfma_f32_16x16x32_bf16 v[44:47], v[92:95], v[216:219], v[44:47]
	s_waitcnt lgkmcnt(2)
	v_mfma_f32_16x16x32_bf16 v[48:51], v[92:95], v[220:223], v[48:51]
	s_waitcnt lgkmcnt(1)
	v_mfma_f32_16x16x32_bf16 v[52:55], v[92:95], v[224:227], v[52:55]
	s_waitcnt lgkmcnt(0)
	v_mfma_f32_16x16x32_bf16 v[56:59], v[92:95], v[228:231], v[56:59]
	ds_read_b128 v[92:95], v0 offset:64
	ds_read_b128 v[180:183], v105 offset:64
	ds_read_b128 v[184:187], v106 offset:64
	ds_read_b128 v[188:191], v106 offset:2368
	ds_read_b128 v[192:195], v106 offset:4672
	ds_read_b128 v[196:199], v106 offset:6976
	ds_read_b128 v[200:203], v106 offset:9280
	ds_read_b128 v[204:207], v106 offset:11584
	ds_read_b128 v[208:211], v106 offset:13888
	ds_read_b128 v[212:215], v105 offset:18496
	ds_read_b128 v[216:219], v105 offset:20800
	ds_read_b128 v[220:223], v105 offset:23104
	ds_read_b128 v[224:227], v105 offset:25408
	ds_read_b128 v[228:231], v105 offset:27712
	s_waitcnt lgkmcnt(12)
	v_mfma_f32_16x16x32_bf16 v[8:11], v[92:95], v[180:183], v[8:11]
	s_waitcnt lgkmcnt(11)
	v_mfma_f32_16x16x32_bf16 v[12:15], v[92:95], v[184:187], v[12:15]
	s_waitcnt lgkmcnt(10)
	v_mfma_f32_16x16x32_bf16 v[16:19], v[92:95], v[188:191], v[16:19]
	s_waitcnt lgkmcnt(9)
	v_mfma_f32_16x16x32_bf16 v[20:23], v[92:95], v[192:195], v[20:23]
	s_waitcnt lgkmcnt(8)
	v_mfma_f32_16x16x32_bf16 v[24:27], v[92:95], v[196:199], v[24:27]
	s_waitcnt lgkmcnt(7)
	v_mfma_f32_16x16x32_bf16 v[28:31], v[92:95], v[200:203], v[28:31]
	s_waitcnt lgkmcnt(6)
	v_mfma_f32_16x16x32_bf16 v[32:35], v[92:95], v[204:207], v[32:35]
	s_waitcnt lgkmcnt(5)
	v_mfma_f32_16x16x32_bf16 v[36:39], v[92:95], v[208:211], v[36:39]
	s_waitcnt lgkmcnt(4)
	v_mfma_f32_16x16x32_bf16 v[40:43], v[92:95], v[212:215], v[40:43]
	s_waitcnt lgkmcnt(3)
	v_mfma_f32_16x16x32_bf16 v[44:47], v[92:95], v[216:219], v[44:47]
	s_waitcnt lgkmcnt(2)
	v_mfma_f32_16x16x32_bf16 v[48:51], v[92:95], v[220:223], v[48:51]
	s_waitcnt lgkmcnt(1)
	v_mfma_f32_16x16x32_bf16 v[52:55], v[92:95], v[224:227], v[52:55]
	s_waitcnt lgkmcnt(0)
	v_mfma_f32_16x16x32_bf16 v[56:59], v[92:95], v[228:231], v[56:59]
	s_cbranch_scc1 .LBB0_1273
	s_mov_b32 s61, s56
	s_branch .LBB0_1267

.Ldil_skipv:
	s_mov_b64 s[52:53], 0
	v_lshl_add_u32 v233, v60, 2, v36
	v_lshl_add_u32 v234, v61, 2, v36
	v_lshl_add_u32 v235, v62, 2, v36
	v_lshl_add_u32 v236, v63, 2, v36
	v_lshl_add_u32 v237, v64, 2, v36
	v_lshl_add_u32 v238, v65, 2, v36
	v_lshl_add_u32 v239, v66, 2, v36
	v_lshl_add_u32 v244, v67, 2, v36
	v_lshl_add_u32 v245, v68, 2, v36
	ds_read_b32 v100, v233 offset:576
	ds_read_b32 v101, v233 offset:580
	ds_read_b32 v102, v233 offset:584
	ds_read_b32 v103, v233 offset:588
	ds_read_b32 v104, v234 offset:576
	ds_read_b32 v105, v234 offset:580
	ds_read_b32 v106, v234 offset:584
	ds_read_b32 v107, v234 offset:588
	ds_read_b32 v108, v235 offset:576
	ds_read_b32 v109, v235 offset:580
	ds_read_b32 v110, v235 offset:584
	ds_read_b32 v111, v235 offset:588
	ds_read_b32 v112, v236 offset:576
	ds_read_b32 v113, v236 offset:580
	ds_read_b32 v114, v236 offset:584
	ds_read_b32 v115, v236 offset:588
	ds_read_b32 v116, v237 offset:576
	ds_read_b32 v117, v237 offset:580
	ds_read_b32 v118, v237 offset:584
	ds_read_b32 v119, v237 offset:588
	ds_read_b32 v204, v238 offset:576
	ds_read_b32 v205, v238 offset:580
	ds_read_b32 v206, v238 offset:584
	ds_read_b32 v207, v238 offset:588
	ds_read_b32 v208, v239 offset:576
	ds_read_b32 v209, v239 offset:580
	ds_read_b32 v210, v239 offset:584
	ds_read_b32 v211, v239 offset:588
	ds_read_b32 v212, v244 offset:576
	ds_read_b32 v213, v244 offset:580
	ds_read_b32 v214, v244 offset:584
	ds_read_b32 v215, v244 offset:588
	ds_read_b32 v216, v245 offset:576
	ds_read_b32 v217, v245 offset:580
	ds_read_b32 v218, v245 offset:584
	ds_read_b32 v219, v245 offset:588
	s_waitcnt lgkmcnt(0)
	v_lshl_add_u32 v80, v60, 2, v36
	v_mov_b32_e32 v78, 0xf149f2ca
	s_and_saveexec_b64 s[28:29], s[30:31]
	s_cbranch_execz .LBB0_1989
	v_mov_b32_e32 v78, v100
	s_waitcnt lgkmcnt(0)
	v_add_f32_e32 v78, v32, v78
.LBB0_1989:
	s_or_b64 exec, exec, s[28:29]
	v_cmp_lt_i32_e64 s[28:29], s62, v49
	v_lshl_add_u32 v81, v61, 2, v36
	s_and_saveexec_b64 s[30:31], s[28:29]
	s_cbranch_execz .LBB0_1991
	v_mov_b32_e32 v32, v104
	s_waitcnt lgkmcnt(0)
	v_add_f32_e32 v77, v28, v32
.LBB0_1991:
	s_or_b64 exec, exec, s[30:31]
	v_cmp_lt_i32_e64 s[30:31], s63, v49
	v_mov_b32_e32 v28, 0xf149f2ca
	v_lshl_add_u32 v82, v62, 2, v36
	v_mov_b32_e32 v32, 0xf149f2ca
	s_and_saveexec_b64 s[34:35], s[30:31]
	s_cbranch_execz .LBB0_1993
	v_mov_b32_e32 v32, v108
	s_waitcnt lgkmcnt(0)
	v_add_f32_e32 v32, v24, v32
.LBB0_1993:
	s_or_b64 exec, exec, s[34:35]
	v_cmp_lt_i32_e64 s[34:35], s64, v49
	v_lshl_add_u32 v83, v63, 2, v36
	s_and_saveexec_b64 s[36:37], s[34:35]
	s_cbranch_execz .LBB0_1995
	v_mov_b32_e32 v24, v112
	s_waitcnt lgkmcnt(0)
	v_add_f32_e32 v28, v12, v24
.LBB0_1995:
	s_or_b64 exec, exec, s[36:37]
	v_cmp_lt_i32_e64 s[36:37], s65, v49
	v_mov_b32_e32 v79, 0xf149f2ca
	v_lshl_add_u32 v84, v64, 2, v36
	v_mov_b32_e32 v87, 0xf149f2ca
	s_and_saveexec_b64 s[38:39], s[36:37]
	s_cbranch_execz .LBB0_1997
	v_mov_b32_e32 v12, v116
	s_waitcnt lgkmcnt(0)
	v_add_f32_e32 v87, v0, v12
.LBB0_1997:
	s_or_b64 exec, exec, s[38:39]
	v_cmp_lt_i32_e64 s[38:39], s66, v49
	v_lshl_add_u32 v85, v65, 2, v36
	s_and_saveexec_b64 s[40:41], s[38:39]
	s_cbranch_execz .LBB0_1999
	v_mov_b32_e32 v0, v204
	s_waitcnt lgkmcnt(0)
	v_add_f32_e32 v79, v8, v0
.LBB0_1999:
	s_or_b64 exec, exec, s[40:41]
	v_cmp_lt_i32_e64 s[40:41], s67, v49
	v_mov_b32_e32 v0, 0xf149f2ca
	v_lshl_add_u32 v86, v66, 2, v36
	v_mov_b32_e32 v8, 0xf149f2ca
	s_and_saveexec_b64 s[42:43], s[40:41]
	s_cbranch_execz .LBB0_2001
	v_mov_b32_e32 v8, v208
	s_waitcnt lgkmcnt(0)
	v_add_f32_e32 v8, v16, v8
.LBB0_2001:
	s_or_b64 exec, exec, s[42:43]
	v_cmp_lt_i32_e64 s[42:43], s33, v49
	v_lshl_add_u32 v88, v67, 2, v36
	s_and_saveexec_b64 s[44:45], s[42:43]
	s_cbranch_execz .LBB0_2003
	v_mov_b32_e32 v0, v212
	s_waitcnt lgkmcnt(0)
	v_add_f32_e32 v0, v20, v0
.LBB0_2003:
	s_or_b64 exec, exec, s[44:45]
	v_mov_b32_e32 v49, 0xf149f2ca
	s_and_saveexec_b64 s[44:45], s[12:13]
	s_cbranch_execz .LBB0_2005
	v_lshl_add_u32 v12, v53, 2, v36
	v_mov_b32_e32 v12, v216
	s_waitcnt lgkmcnt(0)
	v_add_f32_e32 v49, v4, v12

.LBB0_2011:
	s_and_b64 s[46:47], s[14:15], s[26:27]
	v_mov_b32_e32 v4, 0xf149f2ca
	v_mov_b32_e32 v89, 0xf149f2ca
	s_and_saveexec_b64 s[44:45], s[46:47]
	s_cbranch_execz .LBB0_2013
	v_mov_b32_e32 v49, v101
	s_waitcnt lgkmcnt(0)
	v_add_f32_e32 v89, v33, v49
.LBB0_2013:
	s_or_b64 exec, exec, s[44:45]
	s_and_saveexec_b64 s[44:45], s[28:29]
	s_cbranch_execz .LBB0_2015
	v_mov_b32_e32 v4, v105
	s_waitcnt lgkmcnt(0)
	v_add_f32_e32 v4, v29, v4
.LBB0_2015:
	s_or_b64 exec, exec, s[44:45]
	v_mov_b32_e32 v29, 0xf149f2ca
	v_mov_b32_e32 v33, 0xf149f2ca
	s_and_saveexec_b64 s[44:45], s[30:31]
	s_cbranch_execz .LBB0_2017
	v_mov_b32_e32 v33, v109
	s_waitcnt lgkmcnt(0)
	v_add_f32_e32 v33, v25, v33
.LBB0_2017:
	s_or_b64 exec, exec, s[44:45]
	s_and_saveexec_b64 s[44:45], s[34:35]
	s_cbranch_execz .LBB0_2019
	v_mov_b32_e32 v25, v113
	s_waitcnt lgkmcnt(0)
	v_add_f32_e32 v29, v13, v25
.LBB0_2019:
	s_or_b64 exec, exec, s[44:45]
	v_mov_b32_e32 v25, 0xf149f2ca
	v_mov_b32_e32 v90, 0xf149f2ca
	s_and_saveexec_b64 s[44:45], s[36:37]
	s_cbranch_execz .LBB0_2021
	v_mov_b32_e32 v13, v117
	s_waitcnt lgkmcnt(0)
	v_add_f32_e32 v90, v1, v13
.LBB0_2021:
	s_or_b64 exec, exec, s[44:45]
	s_and_saveexec_b64 s[44:45], s[38:39]
	s_cbranch_execz .LBB0_2023
	v_mov_b32_e32 v1, v205
	s_waitcnt lgkmcnt(0)
	v_add_f32_e32 v25, v9, v1
.LBB0_2023:
	s_or_b64 exec, exec, s[44:45]
	v_mov_b32_e32 v9, 0xf149f2ca
	v_mov_b32_e32 v91, 0xf149f2ca
	s_and_saveexec_b64 s[44:45], s[40:41]
	s_cbranch_execz .LBB0_2025
	v_mov_b32_e32 v1, v209
	s_waitcnt lgkmcnt(0)
	v_add_f32_e32 v91, v17, v1
.LBB0_2025:
	s_or_b64 exec, exec, s[44:45]
	s_and_saveexec_b64 s[44:45], s[42:43]
	s_cbranch_execz .LBB0_2027
	v_mov_b32_e32 v1, v213
	s_waitcnt lgkmcnt(0)
	v_add_f32_e32 v9, v21, v1
.LBB0_2027:
	s_or_b64 exec, exec, s[44:45]
	v_mov_b32_e32 v92, 0xf149f2ca
	v_lshl_add_u32 v49, v68, 2, v36
	s_and_saveexec_b64 s[44:45], s[16:17]
	s_cbranch_execz .LBB0_2029
	v_mov_b32_e32 v1, v217
	s_waitcnt lgkmcnt(0)
	v_add_f32_e32 v92, v5, v1

.LBB0_2035:
	s_and_b64 s[84:85], s[18:19], s[26:27]
	v_mov_b32_e32 v89, 0xf149f2ca
	v_mov_b32_e32 v90, 0xf149f2ca
	s_and_saveexec_b64 s[46:47], s[84:85]
	s_cbranch_execz .LBB0_2037
	v_mov_b32_e32 v90, v102
	s_waitcnt lgkmcnt(0)
	v_add_f32_e32 v90, v34, v90
.LBB0_2037:
	s_or_b64 exec, exec, s[46:47]
	s_and_saveexec_b64 s[46:47], s[28:29]
	s_cbranch_execz .LBB0_2039
	v_mov_b32_e32 v34, v106
	s_waitcnt lgkmcnt(0)
	v_add_f32_e32 v89, v30, v34
.LBB0_2039:
	s_or_b64 exec, exec, s[46:47]
	v_mov_b32_e32 v30, 0xf149f2ca
	v_mov_b32_e32 v91, 0xf149f2ca
	s_and_saveexec_b64 s[46:47], s[30:31]
	s_cbranch_execz .LBB0_2041
	v_mov_b32_e32 v34, v110
	s_waitcnt lgkmcnt(0)
	v_add_f32_e32 v91, v26, v34
.LBB0_2041:
	s_or_b64 exec, exec, s[46:47]
	s_and_saveexec_b64 s[46:47], s[34:35]
	s_cbranch_execz .LBB0_2043
	v_mov_b32_e32 v26, v114
	s_waitcnt lgkmcnt(0)
	v_add_f32_e32 v30, v14, v26
.LBB0_2043:
	s_or_b64 exec, exec, s[46:47]
	v_mov_b32_e32 v34, 0xf149f2ca
	v_mov_b32_e32 v92, 0xf149f2ca
	s_and_saveexec_b64 s[46:47], s[36:37]
	s_cbranch_execz .LBB0_2045
	v_mov_b32_e32 v14, v118
	s_waitcnt lgkmcnt(0)
	v_add_f32_e32 v92, v2, v14
.LBB0_2045:
	s_or_b64 exec, exec, s[46:47]
	s_and_saveexec_b64 s[46:47], s[38:39]
	s_cbranch_execz .LBB0_2047
	v_mov_b32_e32 v2, v206
	s_waitcnt lgkmcnt(0)
	v_add_f32_e32 v34, v10, v2
.LBB0_2047:
	s_or_b64 exec, exec, s[46:47]
	v_mov_b32_e32 v2, 0xf149f2ca
	v_mov_b32_e32 v10, 0xf149f2ca
	s_and_saveexec_b64 s[46:47], s[40:41]
	s_cbranch_execz .LBB0_2076
	v_mov_b32_e32 v10, v210
	s_waitcnt lgkmcnt(0)
	v_add_f32_e32 v10, v18, v10
	s_or_b64 exec, exec, s[46:47]
	s_and_saveexec_b64 s[46:47], s[42:43]
	s_cbranch_execnz .LBB0_2077

.LBB0_2050:
	v_mov_b32_e32 v14, v218
	s_waitcnt lgkmcnt(0)
	v_add_f32_e32 v93, v6, v14

.LBB0_2057:
	s_and_b64 s[46:47], s[22:23], s[26:27]
	v_mov_b32_e32 v6, 0xf149f2ca
	v_mov_b32_e32 v92, 0xf149f2ca
	s_and_saveexec_b64 s[26:27], s[46:47]
	s_cbranch_execz .LBB0_2059
	v_mov_b32_e32 v80, v103
	s_waitcnt lgkmcnt(0)
	v_add_f32_e32 v92, v35, v80
.LBB0_2059:
	s_or_b64 exec, exec, s[26:27]
	s_and_saveexec_b64 s[26:27], s[28:29]
	s_cbranch_execz .LBB0_2061
	v_mov_b32_e32 v6, v107
	s_waitcnt lgkmcnt(0)
	v_add_f32_e32 v6, v31, v6
.LBB0_2061:
	s_or_b64 exec, exec, s[26:27]
	v_mov_b32_e32 v31, 0xf149f2ca
	v_mov_b32_e32 v35, 0xf149f2ca
	s_and_saveexec_b64 s[26:27], s[30:31]
	s_cbranch_execz .LBB0_2063
	v_mov_b32_e32 v35, v111
	s_waitcnt lgkmcnt(0)
	v_add_f32_e32 v35, v27, v35
.LBB0_2063:
	s_or_b64 exec, exec, s[26:27]
	s_and_saveexec_b64 s[26:27], s[34:35]
	s_cbranch_execz .LBB0_2065
	v_mov_b32_e32 v27, v115
	s_waitcnt lgkmcnt(0)
	v_add_f32_e32 v31, v15, v27
.LBB0_2065:
	s_or_b64 exec, exec, s[26:27]
	v_mov_b32_e32 v27, 0xf149f2ca
	v_mov_b32_e32 v80, 0xf149f2ca
	s_and_saveexec_b64 s[26:27], s[36:37]
	s_cbranch_execz .LBB0_2067
	v_mov_b32_e32 v15, v119
	s_waitcnt lgkmcnt(0)
	v_add_f32_e32 v80, v3, v15
.LBB0_2067:
	s_or_b64 exec, exec, s[26:27]
	s_and_saveexec_b64 s[26:27], s[38:39]
	s_cbranch_execz .LBB0_2069
	v_mov_b32_e32 v3, v207
	s_waitcnt lgkmcnt(0)
	v_add_f32_e32 v27, v11, v3
.LBB0_2069:
	s_or_b64 exec, exec, s[26:27]
	v_mov_b32_e32 v11, 0xf149f2ca
	v_mov_b32_e32 v81, 0xf149f2ca
	s_and_saveexec_b64 s[26:27], s[40:41]
	s_cbranch_execz .LBB0_2078
	v_mov_b32_e32 v3, v211
	s_waitcnt lgkmcnt(0)
	v_add_f32_e32 v81, v19, v3
	s_or_b64 exec, exec, s[26:27]
	s_and_saveexec_b64 s[26:27], s[42:43]
	s_cbranch_execnz .LBB0_2079

.LBB0_2072:
	v_mov_b32_e32 v3, v219
	s_waitcnt lgkmcnt(0)
	v_add_f32_e32 v82, v7, v3

.LBB0_2077:
	v_mov_b32_e32 v2, v214
	s_waitcnt lgkmcnt(0)
	v_add_f32_e32 v2, v22, v2
	s_or_b64 exec, exec, s[46:47]
	v_mov_b32_e32 v93, 0xf149f2ca
	s_and_saveexec_b64 s[46:47], s[20:21]
	s_cbranch_execnz .LBB0_2050
	s_branch .LBB0_2051

.LBB0_2079:
	v_mov_b32_e32 v3, v215
	s_waitcnt lgkmcnt(0)
	v_add_f32_e32 v11, v23, v3
	s_or_b64 exec, exec, s[26:27]
	v_mov_b32_e32 v82, 0xf149f2ca
	s_and_saveexec_b64 s[26:27], s[24:25]
	s_cbranch_execnz .LBB0_2072
	s_branch .LBB0_2073
